# sample_attn K-phase and ssm_sample: the 16 independent wave reductions batched (same butterfly order), d_skip fetched once per sample
# speedup vs baseline: 1.0094x; 1.0094x over previous
.LBB11_791:
	global_load_dword v44, v1, s[46:47]
	s_add_u32 s0, s88, 0x15900000
	s_addc_u32 s1, s89, 0
	s_add_u32 s6, s88, 0x11800000
	s_addc_u32 s7, s89, 0
	v_mov_b32_e32 v91, 0
	s_waitcnt vmcnt(0)
	v_fmamk_f32 v44, v44, 0x3a800000, v206
	v_cmp_gt_f32_e64 s[44:45], s77, v44
	v_mul_f32_e32 v45, 0x4b800000, v44
	s_nop 0
	v_cndmask_b32_e64 v44, v44, v45, s[44:45]
	v_rsq_f32_e32 v44, v44
	s_nop 0
	v_mul_f32_e32 v45, 0x45800000, v44
	v_cndmask_b32_e64 v112, v44, v45, s[44:45]
	s_waitcnt lgkmcnt(0)
	global_load_dwordx4 v[44:47], v1, s[0:1] offset:16
	global_load_dwordx4 v[48:51], v209, s[88:89]
	global_load_dwordx4 v[92:95], v1, s[6:7] offset:16
	global_load_dwordx4 v[52:55], v210, s[88:89]
	global_load_dwordx4 v[96:99], v1, s[56:57] offset:48
	global_load_dwordx4 v[100:103], v1, s[56:57] offset:32
	global_load_dwordx4 v[104:107], v1, s[56:57] offset:16
	global_load_dwordx4 v[108:111], v1, s[56:57]
	s_mov_b32 s0, 0x8100000
	s_waitcnt vmcnt(6)
	v_lshlrev_b32_e32 v56, 16, v48
	v_and_b32_e32 v57, 0xffff0000, v48
	s_waitcnt vmcnt(4)
	v_lshlrev_b32_e32 v58, 16, v52
	v_and_b32_e32 v59, 0xffff0000, v52
	v_lshlrev_b32_e32 v48, 16, v49
	v_and_b32_e32 v49, 0xffff0000, v49
	v_lshlrev_b32_e32 v52, 16, v53
	v_and_b32_e32 v53, 0xffff0000, v53
	v_pk_add_f32 v[56:57], v[56:57], v[58:59]
	v_pk_add_f32 v[48:49], v[48:49], v[52:53]
	v_pk_mul_f32 v[52:53], v[112:113], v[56:57] op_sel_hi:[0,1]
	v_pk_mul_f32 v[48:49], v[112:113], v[48:49] op_sel_hi:[0,1]
	s_waitcnt vmcnt(0)
	v_pk_mul_f32 v[56:57], v[110:111], v[48:49]
	v_pk_mul_f32 v[58:59], v[108:109], v[52:53]
	v_lshlrev_b32_e32 v48, 16, v50
	v_and_b32_e32 v49, 0xffff0000, v50
	v_lshlrev_b32_e32 v52, 16, v54
	v_and_b32_e32 v53, 0xffff0000, v54
	v_pk_add_f32 v[48:49], v[48:49], v[52:53]
	v_lshlrev_b32_e32 v50, 16, v51
	v_and_b32_e32 v51, 0xffff0000, v51
	v_lshlrev_b32_e32 v52, 16, v55
	v_and_b32_e32 v53, 0xffff0000, v55
	v_pk_add_f32 v[50:51], v[50:51], v[52:53]
	v_pk_mul_f32 v[48:49], v[112:113], v[48:49] op_sel_hi:[0,1]
	v_pk_mul_f32 v[50:51], v[112:113], v[50:51] op_sel_hi:[0,1]
	v_pk_mul_f32 v[52:53], v[106:107], v[50:51]
	v_pk_mul_f32 v[54:55], v[104:105], v[48:49]
	v_lshlrev_b32_e32 v48, 16, v44
	v_and_b32_e32 v49, 0xffff0000, v44
	v_lshlrev_b32_e32 v50, 16, v92
	v_and_b32_e32 v51, 0xffff0000, v92
	v_pk_add_f32 v[48:49], v[48:49], v[50:51]
	v_lshlrev_b32_e32 v44, 16, v45
	v_and_b32_e32 v45, 0xffff0000, v45
	v_lshlrev_b32_e32 v50, 16, v93
	v_and_b32_e32 v51, 0xffff0000, v93
	v_pk_add_f32 v[44:45], v[44:45], v[50:51]
	v_pk_mul_f32 v[50:51], v[112:113], v[48:49] op_sel_hi:[0,1]
	v_pk_mul_f32 v[44:45], v[112:113], v[44:45] op_sel_hi:[0,1]
	v_pk_mul_f32 v[48:49], v[102:103], v[44:45]
	v_lshlrev_b32_e32 v44, 16, v46
	v_and_b32_e32 v45, 0xffff0000, v46
	v_lshlrev_b32_e32 v92, 16, v94
	v_and_b32_e32 v93, 0xffff0000, v94
	v_pk_add_f32 v[44:45], v[44:45], v[92:93]
	v_lshlrev_b32_e32 v46, 16, v47
	v_and_b32_e32 v47, 0xffff0000, v47
	v_lshlrev_b32_e32 v92, 16, v95
	v_and_b32_e32 v93, 0xffff0000, v95
	v_pk_add_f32 v[46:47], v[46:47], v[92:93]
	v_pk_mul_f32 v[92:93], v[112:113], v[44:45] op_sel_hi:[0,1]
	v_lshl_add_u64 v[94:95], v[40:41], 0, s[90:91]
	v_pk_mul_f32 v[44:45], v[112:113], v[46:47] op_sel_hi:[0,1]
	v_pk_mul_f32 v[46:47], v[96:97], v[92:93]
	global_load_dword v96, v[94:95], off
	v_lshl_add_u64 v[94:95], v[38:39], 0, s[90:91]
	global_load_dword v94, v[94:95], off
	v_fma_f32 v93, v2, v58, 0
	v_fma_f32 v92, v3, v58, 0
	v_fmac_f32_e32 v93, v4, v59
	v_fmac_f32_e32 v92, v5, v59
	v_fmac_f32_e32 v93, v6, v56
	v_fmac_f32_e32 v92, v7, v56
	v_fmac_f32_e32 v93, v8, v57
	v_fmac_f32_e32 v92, v9, v57
	v_fmac_f32_e32 v93, v10, v54
	v_fmac_f32_e32 v92, v11, v54
	v_fmac_f32_e32 v93, v12, v55
	v_fmac_f32_e32 v92, v13, v55
	v_fmac_f32_e32 v93, v14, v52
	v_fmac_f32_e32 v92, v15, v52
	v_pk_mul_f32 v[50:51], v[100:101], v[50:51]
	v_fmac_f32_e32 v93, v16, v53
	v_fmac_f32_e32 v92, v17, v53
	v_fmac_f32_e32 v93, v18, v50
	v_fmac_f32_e32 v92, v19, v50
	v_fmac_f32_e32 v93, v20, v51
	v_fmac_f32_e32 v92, v21, v51
	v_fmac_f32_e32 v93, v22, v48
	v_fmac_f32_e32 v92, v23, v48
	v_fmac_f32_e32 v93, v24, v49
	v_fmac_f32_e32 v92, v25, v49
	v_fmac_f32_e32 v93, v26, v46
	v_fmac_f32_e32 v92, v27, v46
	v_pk_mul_f32 v[44:45], v[98:99], v[44:45]
	v_fmac_f32_e32 v93, v28, v47
	v_fmac_f32_e32 v92, v29, v47
	v_fmac_f32_e32 v93, v30, v44
	v_fmac_f32_e32 v92, v31, v44
	v_fmac_f32_e32 v93, v32, v45
	v_fmac_f32_e32 v92, v33, v45
	s_waitcnt vmcnt(0)
	v_mul_f32_e32 v95, v35, v94
	v_mul_f32_e32 v94, v34, v94
	v_fma_f32 v95, v34, v96, -v95
	v_fmac_f32_e32 v94, v35, v96
	v_add_f32_e32 v93, v95, v93
	v_add_f32_e32 v92, v94, v92
	v_lshl_add_u64 v[94:95], v[36:37], 0, s[90:91]
	v_add_co_u32_e64 v96, s[44:45], s0, v94
	s_mov_b32 s0, 0x8500000
	s_nop 0
	v_addc_co_u32_e64 v97, s[44:45], 0, v95, s[44:45]
	v_add_co_u32_e64 v94, s[44:45], s0, v94
	global_store_dword v[96:97], v93, off
	s_nop 0
	v_addc_co_u32_e64 v95, s[44:45], 0, v95, s[44:45]
	global_store_dword v[94:95], v92, off
	s_load_dwordx2 s[0:1], s[58:59], 0xc8
	s_lshl_b64 s[6:7], s[60:61], 2
	v_mbcnt_lo_u32_b32 v231, -1, 0
	v_mbcnt_hi_u32_b32 v231, -1, v231
	v_lshlrev_b32_e32 v231, 2, v231
	s_waitcnt lgkmcnt(0)
	s_add_u32 s0, s0, s6
	s_addc_u32 s1, s1, s7
	s_and_saveexec_b64 s[44:45], vcc
	global_load_dword v230, v231, s[0:1]
	s_or_b64 exec, exec, s[44:45]
	v_mul_f32_e32 v214, v67, v92
	v_fma_f32 v214, v0, v93, -v214
	v_mul_f32_e32 v215, v68, v92
	v_fma_f32 v215, v60, v93, -v215
	v_mul_f32_e32 v216, v69, v92
	v_fma_f32 v216, v61, v93, -v216
	v_mul_f32_e32 v217, v70, v92
	v_fma_f32 v217, v62, v93, -v217
	v_mul_f32_e32 v218, v71, v92
	v_fma_f32 v218, v63, v93, -v218
	v_mul_f32_e32 v219, v72, v92
	v_fma_f32 v219, v64, v93, -v219
	v_mul_f32_e32 v220, v73, v92
	v_fma_f32 v220, v65, v93, -v220
	v_mul_f32_e32 v221, v74, v92
	v_fma_f32 v221, v66, v93, -v221
	v_mul_f32_e32 v222, v83, v92
	v_fma_f32 v222, v75, v93, -v222
	v_mul_f32_e32 v223, v84, v92
	v_fma_f32 v223, v76, v93, -v223
	v_mul_f32_e32 v224, v85, v92
	v_fma_f32 v224, v77, v93, -v224
	v_mul_f32_e32 v225, v86, v92
	v_fma_f32 v225, v78, v93, -v225
	v_mul_f32_e32 v226, v87, v92
	v_fma_f32 v226, v79, v93, -v226
	v_mul_f32_e32 v227, v88, v92
	v_fma_f32 v227, v80, v93, -v227
	v_mul_f32_e32 v228, v89, v92
	v_fma_f32 v228, v81, v93, -v228
	v_mul_f32_e32 v229, v90, v92
	v_fma_f32 v229, v82, v93, -v229
	ds_bpermute_b32 v116, v200, v214
	ds_bpermute_b32 v117, v200, v215
	ds_bpermute_b32 v118, v200, v216
	ds_bpermute_b32 v119, v200, v217
	ds_bpermute_b32 v120, v200, v218
	ds_bpermute_b32 v121, v200, v219
	ds_bpermute_b32 v122, v200, v220
	ds_bpermute_b32 v123, v200, v221
	s_waitcnt lgkmcnt(7)
	v_add_f32_e32 v214, v214, v116
	s_waitcnt lgkmcnt(6)
	v_add_f32_e32 v215, v215, v117
	s_waitcnt lgkmcnt(5)
	v_add_f32_e32 v216, v216, v118
	s_waitcnt lgkmcnt(4)
	v_add_f32_e32 v217, v217, v119
	s_waitcnt lgkmcnt(3)
	v_add_f32_e32 v218, v218, v120
	s_waitcnt lgkmcnt(2)
	v_add_f32_e32 v219, v219, v121
	s_waitcnt lgkmcnt(1)
	v_add_f32_e32 v220, v220, v122
	s_waitcnt lgkmcnt(0)
	v_add_f32_e32 v221, v221, v123
	ds_bpermute_b32 v116, v201, v214
	ds_bpermute_b32 v117, v201, v215
	ds_bpermute_b32 v118, v201, v216
	ds_bpermute_b32 v119, v201, v217
	ds_bpermute_b32 v120, v201, v218
	ds_bpermute_b32 v121, v201, v219
	ds_bpermute_b32 v122, v201, v220
	ds_bpermute_b32 v123, v201, v221
	s_waitcnt lgkmcnt(7)
	v_add_f32_e32 v214, v214, v116
	s_waitcnt lgkmcnt(6)
	v_add_f32_e32 v215, v215, v117
	s_waitcnt lgkmcnt(5)
	v_add_f32_e32 v216, v216, v118
	s_waitcnt lgkmcnt(4)
	v_add_f32_e32 v217, v217, v119
	s_waitcnt lgkmcnt(3)
	v_add_f32_e32 v218, v218, v120
	s_waitcnt lgkmcnt(2)
	v_add_f32_e32 v219, v219, v121
	s_waitcnt lgkmcnt(1)
	v_add_f32_e32 v220, v220, v122
	s_waitcnt lgkmcnt(0)
	v_add_f32_e32 v221, v221, v123
	ds_bpermute_b32 v116, v202, v214
	ds_bpermute_b32 v117, v202, v215
	ds_bpermute_b32 v118, v202, v216
	ds_bpermute_b32 v119, v202, v217
	ds_bpermute_b32 v120, v202, v218
	ds_bpermute_b32 v121, v202, v219
	ds_bpermute_b32 v122, v202, v220
	ds_bpermute_b32 v123, v202, v221
	s_waitcnt lgkmcnt(7)
	v_add_f32_e32 v214, v214, v116
	s_waitcnt lgkmcnt(6)
	v_add_f32_e32 v215, v215, v117
	s_waitcnt lgkmcnt(5)
	v_add_f32_e32 v216, v216, v118
	s_waitcnt lgkmcnt(4)
	v_add_f32_e32 v217, v217, v119
	s_waitcnt lgkmcnt(3)
	v_add_f32_e32 v218, v218, v120
	s_waitcnt lgkmcnt(2)
	v_add_f32_e32 v219, v219, v121
	s_waitcnt lgkmcnt(1)
	v_add_f32_e32 v220, v220, v122
	s_waitcnt lgkmcnt(0)
	v_add_f32_e32 v221, v221, v123
	ds_bpermute_b32 v116, v203, v214
	ds_bpermute_b32 v117, v203, v215
	ds_bpermute_b32 v118, v203, v216
	ds_bpermute_b32 v119, v203, v217
	ds_bpermute_b32 v120, v203, v218
	ds_bpermute_b32 v121, v203, v219
	ds_bpermute_b32 v122, v203, v220
	ds_bpermute_b32 v123, v203, v221
	s_waitcnt lgkmcnt(7)
	v_add_f32_e32 v214, v214, v116
	s_waitcnt lgkmcnt(6)
	v_add_f32_e32 v215, v215, v117
	s_waitcnt lgkmcnt(5)
	v_add_f32_e32 v216, v216, v118
	s_waitcnt lgkmcnt(4)
	v_add_f32_e32 v217, v217, v119
	s_waitcnt lgkmcnt(3)
	v_add_f32_e32 v218, v218, v120
	s_waitcnt lgkmcnt(2)
	v_add_f32_e32 v219, v219, v121
	s_waitcnt lgkmcnt(1)
	v_add_f32_e32 v220, v220, v122
	s_waitcnt lgkmcnt(0)
	v_add_f32_e32 v221, v221, v123
	ds_bpermute_b32 v116, v204, v214
	ds_bpermute_b32 v117, v204, v215
	ds_bpermute_b32 v118, v204, v216
	ds_bpermute_b32 v119, v204, v217
	ds_bpermute_b32 v120, v204, v218
	ds_bpermute_b32 v121, v204, v219
	ds_bpermute_b32 v122, v204, v220
	ds_bpermute_b32 v123, v204, v221
	s_waitcnt lgkmcnt(7)
	v_add_f32_e32 v214, v214, v116
	s_waitcnt lgkmcnt(6)
	v_add_f32_e32 v215, v215, v117
	s_waitcnt lgkmcnt(5)
	v_add_f32_e32 v216, v216, v118
	s_waitcnt lgkmcnt(4)
	v_add_f32_e32 v217, v217, v119
	s_waitcnt lgkmcnt(3)
	v_add_f32_e32 v218, v218, v120
	s_waitcnt lgkmcnt(2)
	v_add_f32_e32 v219, v219, v121
	s_waitcnt lgkmcnt(1)
	v_add_f32_e32 v220, v220, v122
	s_waitcnt lgkmcnt(0)
	v_add_f32_e32 v221, v221, v123
	ds_bpermute_b32 v116, v205, v214
	ds_bpermute_b32 v117, v205, v215
	ds_bpermute_b32 v118, v205, v216
	ds_bpermute_b32 v119, v205, v217
	ds_bpermute_b32 v120, v205, v218
	ds_bpermute_b32 v121, v205, v219
	ds_bpermute_b32 v122, v205, v220
	ds_bpermute_b32 v123, v205, v221
	s_waitcnt lgkmcnt(7)
	v_add_f32_e32 v214, v214, v116
	s_waitcnt lgkmcnt(6)
	v_add_f32_e32 v215, v215, v117
	s_waitcnt lgkmcnt(5)
	v_add_f32_e32 v216, v216, v118
	s_waitcnt lgkmcnt(4)
	v_add_f32_e32 v217, v217, v119
	s_waitcnt lgkmcnt(3)
	v_add_f32_e32 v218, v218, v120
	s_waitcnt lgkmcnt(2)
	v_add_f32_e32 v219, v219, v121
	s_waitcnt lgkmcnt(1)
	v_add_f32_e32 v220, v220, v122
	s_waitcnt lgkmcnt(0)
	v_add_f32_e32 v221, v221, v123
	ds_bpermute_b32 v124, v200, v222
	ds_bpermute_b32 v125, v200, v223
	ds_bpermute_b32 v126, v200, v224
	ds_bpermute_b32 v127, v200, v225
	ds_bpermute_b32 v128, v200, v226
	ds_bpermute_b32 v129, v200, v227
	ds_bpermute_b32 v130, v200, v228
	ds_bpermute_b32 v131, v200, v229
	s_waitcnt lgkmcnt(7)
	v_add_f32_e32 v222, v222, v124
	s_waitcnt lgkmcnt(6)
	v_add_f32_e32 v223, v223, v125
	s_waitcnt lgkmcnt(5)
	v_add_f32_e32 v224, v224, v126
	s_waitcnt lgkmcnt(4)
	v_add_f32_e32 v225, v225, v127
	s_waitcnt lgkmcnt(3)
	v_add_f32_e32 v226, v226, v128
	s_waitcnt lgkmcnt(2)
	v_add_f32_e32 v227, v227, v129
	s_waitcnt lgkmcnt(1)
	v_add_f32_e32 v228, v228, v130
	s_waitcnt lgkmcnt(0)
	v_add_f32_e32 v229, v229, v131
	ds_bpermute_b32 v124, v201, v222
	ds_bpermute_b32 v125, v201, v223
	ds_bpermute_b32 v126, v201, v224
	ds_bpermute_b32 v127, v201, v225
	ds_bpermute_b32 v128, v201, v226
	ds_bpermute_b32 v129, v201, v227
	ds_bpermute_b32 v130, v201, v228
	ds_bpermute_b32 v131, v201, v229
	s_waitcnt lgkmcnt(7)
	v_add_f32_e32 v222, v222, v124
	s_waitcnt lgkmcnt(6)
	v_add_f32_e32 v223, v223, v125
	s_waitcnt lgkmcnt(5)
	v_add_f32_e32 v224, v224, v126
	s_waitcnt lgkmcnt(4)
	v_add_f32_e32 v225, v225, v127
	s_waitcnt lgkmcnt(3)
	v_add_f32_e32 v226, v226, v128
	s_waitcnt lgkmcnt(2)
	v_add_f32_e32 v227, v227, v129
	s_waitcnt lgkmcnt(1)
	v_add_f32_e32 v228, v228, v130
	s_waitcnt lgkmcnt(0)
	v_add_f32_e32 v229, v229, v131
	ds_bpermute_b32 v124, v202, v222
	ds_bpermute_b32 v125, v202, v223
	ds_bpermute_b32 v126, v202, v224
	ds_bpermute_b32 v127, v202, v225
	ds_bpermute_b32 v128, v202, v226
	ds_bpermute_b32 v129, v202, v227
	ds_bpermute_b32 v130, v202, v228
	ds_bpermute_b32 v131, v202, v229
	s_waitcnt lgkmcnt(7)
	v_add_f32_e32 v222, v222, v124
	s_waitcnt lgkmcnt(6)
	v_add_f32_e32 v223, v223, v125
	s_waitcnt lgkmcnt(5)
	v_add_f32_e32 v224, v224, v126
	s_waitcnt lgkmcnt(4)
	v_add_f32_e32 v225, v225, v127
	s_waitcnt lgkmcnt(3)
	v_add_f32_e32 v226, v226, v128
	s_waitcnt lgkmcnt(2)
	v_add_f32_e32 v227, v227, v129
	s_waitcnt lgkmcnt(1)
	v_add_f32_e32 v228, v228, v130
	s_waitcnt lgkmcnt(0)
	v_add_f32_e32 v229, v229, v131
	ds_bpermute_b32 v124, v203, v222
	ds_bpermute_b32 v125, v203, v223
	ds_bpermute_b32 v126, v203, v224
	ds_bpermute_b32 v127, v203, v225
	ds_bpermute_b32 v128, v203, v226
	ds_bpermute_b32 v129, v203, v227
	ds_bpermute_b32 v130, v203, v228
	ds_bpermute_b32 v131, v203, v229
	s_waitcnt lgkmcnt(7)
	v_add_f32_e32 v222, v222, v124
	s_waitcnt lgkmcnt(6)
	v_add_f32_e32 v223, v223, v125
	s_waitcnt lgkmcnt(5)
	v_add_f32_e32 v224, v224, v126
	s_waitcnt lgkmcnt(4)
	v_add_f32_e32 v225, v225, v127
	s_waitcnt lgkmcnt(3)
	v_add_f32_e32 v226, v226, v128
	s_waitcnt lgkmcnt(2)
	v_add_f32_e32 v227, v227, v129
	s_waitcnt lgkmcnt(1)
	v_add_f32_e32 v228, v228, v130
	s_waitcnt lgkmcnt(0)
	v_add_f32_e32 v229, v229, v131
	ds_bpermute_b32 v124, v204, v222
	ds_bpermute_b32 v125, v204, v223
	ds_bpermute_b32 v126, v204, v224
	ds_bpermute_b32 v127, v204, v225
	ds_bpermute_b32 v128, v204, v226
	ds_bpermute_b32 v129, v204, v227
	ds_bpermute_b32 v130, v204, v228
	ds_bpermute_b32 v131, v204, v229
	s_waitcnt lgkmcnt(7)
	v_add_f32_e32 v222, v222, v124
	s_waitcnt lgkmcnt(6)
	v_add_f32_e32 v223, v223, v125
	s_waitcnt lgkmcnt(5)
	v_add_f32_e32 v224, v224, v126
	s_waitcnt lgkmcnt(4)
	v_add_f32_e32 v225, v225, v127
	s_waitcnt lgkmcnt(3)
	v_add_f32_e32 v226, v226, v128
	s_waitcnt lgkmcnt(2)
	v_add_f32_e32 v227, v227, v129
	s_waitcnt lgkmcnt(1)
	v_add_f32_e32 v228, v228, v130
	s_waitcnt lgkmcnt(0)
	v_add_f32_e32 v229, v229, v131
	ds_bpermute_b32 v124, v205, v222
	ds_bpermute_b32 v125, v205, v223
	ds_bpermute_b32 v126, v205, v224
	ds_bpermute_b32 v127, v205, v225
	ds_bpermute_b32 v128, v205, v226
	ds_bpermute_b32 v129, v205, v227
	ds_bpermute_b32 v130, v205, v228
	ds_bpermute_b32 v131, v205, v229
	s_waitcnt lgkmcnt(7)
	v_add_f32_e32 v222, v222, v124
	s_waitcnt lgkmcnt(6)
	v_add_f32_e32 v223, v223, v125
	s_waitcnt lgkmcnt(5)
	v_add_f32_e32 v224, v224, v126
	s_waitcnt lgkmcnt(4)
	v_add_f32_e32 v225, v225, v127
	s_waitcnt lgkmcnt(3)
	v_add_f32_e32 v226, v226, v128
	s_waitcnt lgkmcnt(2)
	v_add_f32_e32 v227, v227, v129
	s_waitcnt lgkmcnt(1)
	v_add_f32_e32 v228, v228, v130
	s_waitcnt lgkmcnt(0)
	v_add_f32_e32 v229, v229, v131
	s_waitcnt vmcnt(0)
	s_and_saveexec_b64 s[44:45], s[10:11]
	v_fma_f32 v91, v58, v230, v214
	s_or_b64 exec, exec, s[44:45]
	s_and_saveexec_b64 s[44:45], s[12:13]
	v_fma_f32 v91, v59, v230, v215
	s_or_b64 exec, exec, s[44:45]
	s_and_saveexec_b64 s[44:45], s[14:15]
	v_fma_f32 v91, v56, v230, v216
	s_or_b64 exec, exec, s[44:45]
	s_and_saveexec_b64 s[44:45], s[16:17]
	v_fma_f32 v91, v57, v230, v217
	s_or_b64 exec, exec, s[44:45]
	s_and_saveexec_b64 s[44:45], s[18:19]
	v_fma_f32 v91, v54, v230, v218
	s_or_b64 exec, exec, s[44:45]
	s_and_saveexec_b64 s[44:45], s[20:21]
	v_fma_f32 v91, v55, v230, v219
	s_or_b64 exec, exec, s[44:45]
	s_and_saveexec_b64 s[44:45], s[22:23]
	v_fma_f32 v91, v52, v230, v220
	s_or_b64 exec, exec, s[44:45]
	s_and_saveexec_b64 s[44:45], s[24:25]
	v_fma_f32 v91, v53, v230, v221
	s_or_b64 exec, exec, s[44:45]
	s_and_saveexec_b64 s[44:45], s[26:27]
	v_fma_f32 v91, v50, v230, v222
	s_or_b64 exec, exec, s[44:45]
	s_and_saveexec_b64 s[44:45], s[28:29]
	v_fma_f32 v91, v51, v230, v223
	s_or_b64 exec, exec, s[44:45]
	s_and_saveexec_b64 s[44:45], s[30:31]
	v_fma_f32 v91, v48, v230, v224
	s_or_b64 exec, exec, s[44:45]
	s_and_saveexec_b64 s[44:45], s[34:35]
	v_fma_f32 v91, v49, v230, v225
	s_or_b64 exec, exec, s[44:45]
	s_and_saveexec_b64 s[44:45], s[36:37]
	v_fma_f32 v91, v46, v230, v226
	s_or_b64 exec, exec, s[44:45]
	s_and_saveexec_b64 s[44:45], s[38:39]
	v_fma_f32 v91, v47, v230, v227
	s_or_b64 exec, exec, s[44:45]
	s_and_saveexec_b64 s[44:45], s[40:41]
	v_fma_f32 v91, v44, v230, v228
	s_or_b64 exec, exec, s[44:45]
	s_and_saveexec_b64 s[44:45], s[42:43]
	v_fma_f32 v91, v45, v230, v229
	s_or_b64 exec, exec, s[44:45]
	s_and_saveexec_b64 s[44:45], vcc
	s_cbranch_execz .LBB11_790
	v_mul_f32_e32 v44, 0x3d922279, v91
	v_fmaak_f32 v44, v91, v44, 0x3fcc422a
	v_mul_f32_e32 v44, v91, v44
	v_mul_f32_e32 v44, 0xbfb8aa3b, v44
	v_exp_f32_e32 v44, v44
	s_nop 0
	v_add_f32_e32 v44, 1.0, v44
	v_rcp_f32_e32 v44, v44
	s_nop 0
	v_mul_f32_e32 v44, v91, v44
	s_waitcnt lgkmcnt(0)
	v_cvt_pk_bf16_f32 v46, v44, v1
	v_lshl_add_u64 v[44:45], s[88:89], 0, v[42:43]
	global_store_short v[44:45], v46, off
	s_branch .LBB11_790

.LBB11_2193:
	s_lshl_b32 s1, s0, 4
	s_or_b32 s60, s1, s76
	s_lshl_b64 s[48:49], s[60:61], 12
	s_waitcnt lgkmcnt(0)
	v_lshl_add_u64 v[2:3], v[62:63], 0, s[48:49]
	s_or_b32 s48, s60, 1
	s_mov_b32 s49, s61
	s_lshl_b64 s[48:49], s[48:49], 12
	v_lshl_add_u64 v[4:5], v[62:63], 0, s[48:49]
	global_load_dwordx4 v[68:71], v[2:3], off nt
	global_load_dwordx4 v[58:61], v[4:5], off nt
	s_or_b32 s48, s60, 2
	s_mov_b32 s49, s61
	s_lshl_b64 s[48:49], s[48:49], 12
	v_lshl_add_u64 v[2:3], v[62:63], 0, s[48:49]
	s_or_b32 s48, s60, 3
	s_mov_b32 s49, s61
	s_lshl_b64 s[48:49], s[48:49], 12
	v_lshl_add_u64 v[4:5], v[62:63], 0, s[48:49]
	s_or_b32 s48, s60, 4
	s_mov_b32 s49, s61
	s_lshl_b64 s[48:49], s[48:49], 12
	global_load_dwordx4 v[54:57], v[2:3], off nt
	global_load_dwordx4 v[50:53], v[4:5], off nt
	v_lshl_add_u64 v[2:3], v[62:63], 0, s[48:49]
	s_or_b32 s48, s60, 5
	s_mov_b32 s49, s61
	s_lshl_b64 s[48:49], s[48:49], 12
	v_lshl_add_u64 v[4:5], v[62:63], 0, s[48:49]
	s_or_b32 s48, s60, 6
	s_mov_b32 s49, s61
	s_lshl_b64 s[48:49], s[48:49], 12
	global_load_dwordx4 v[46:49], v[2:3], off nt
	global_load_dwordx4 v[42:45], v[4:5], off nt
	v_lshl_add_u64 v[2:3], v[62:63], 0, s[48:49]
	s_or_b32 s48, s60, 7
	s_mov_b32 s49, s61
	s_lshl_b64 s[48:49], s[48:49], 12
	v_lshl_add_u64 v[4:5], v[62:63], 0, s[48:49]
	s_or_b32 s48, s60, 8
	s_mov_b32 s49, s61
	s_lshl_b64 s[48:49], s[48:49], 12
	global_load_dwordx4 v[38:41], v[2:3], off nt
	global_load_dwordx4 v[34:37], v[4:5], off nt
	v_lshl_add_u64 v[2:3], v[62:63], 0, s[48:49]
	s_or_b32 s48, s60, 9
	s_mov_b32 s49, s61
	s_lshl_b64 s[48:49], s[48:49], 12
	v_lshl_add_u64 v[4:5], v[62:63], 0, s[48:49]
	s_or_b32 s48, s60, 10
	s_mov_b32 s49, s61
	s_lshl_b64 s[48:49], s[48:49], 12
	global_load_dwordx4 v[30:33], v[2:3], off nt
	global_load_dwordx4 v[26:29], v[4:5], off nt
	v_lshl_add_u64 v[2:3], v[62:63], 0, s[48:49]
	s_or_b32 s48, s60, 11
	s_mov_b32 s49, s61
	s_lshl_b64 s[48:49], s[48:49], 12
	v_lshl_add_u64 v[4:5], v[62:63], 0, s[48:49]
	s_or_b32 s48, s60, 12
	s_mov_b32 s49, s61
	s_lshl_b64 s[48:49], s[48:49], 12
	global_load_dwordx4 v[22:25], v[2:3], off nt
	global_load_dwordx4 v[18:21], v[4:5], off nt
	v_lshl_add_u64 v[2:3], v[62:63], 0, s[48:49]
	s_or_b32 s48, s60, 13
	s_mov_b32 s49, s61
	s_lshl_b64 s[48:49], s[48:49], 12
	v_lshl_add_u64 v[4:5], v[62:63], 0, s[48:49]
	s_or_b32 s48, s60, 14
	s_mov_b32 s49, s61
	s_lshl_b64 s[48:49], s[48:49], 12
	s_or_b32 s60, s60, 15
	global_load_dwordx4 v[14:17], v[2:3], off nt
	global_load_dwordx4 v[10:13], v[4:5], off nt
	v_lshl_add_u64 v[2:3], v[62:63], 0, s[48:49]
	s_lshl_b64 s[48:49], s[60:61], 12
	v_lshl_add_u64 v[4:5], v[62:63], 0, s[48:49]
	global_load_dwordx4 v[6:9], v[2:3], off nt
	s_nop 0
	global_load_dwordx4 v[2:5], v[4:5], off nt
	s_lshl_b32 s60, s0, 6
	s_waitcnt vmcnt(15)
	v_mul_f32_e32 v69, v69, v65
	v_mul_f32_e32 v71, v71, v67
	v_fmac_f32_e32 v69, v68, v64
	v_fmac_f32_e32 v71, v70, v66
	v_add_f32_e32 v68, v69, v71
	s_waitcnt vmcnt(14)
	v_mul_f32_e32 v59, v59, v65
	v_fmac_f32_e32 v59, v58, v64
	v_mul_f32_e32 v58, v61, v67
	v_fmac_f32_e32 v58, v60, v66
	v_add_f32_e32 v58, v59, v58
	s_waitcnt vmcnt(13)
	v_mul_f32_e32 v55, v55, v65
	v_fmac_f32_e32 v55, v54, v64
	v_mul_f32_e32 v54, v57, v67
	v_fmac_f32_e32 v54, v56, v66
	v_add_f32_e32 v54, v55, v54
	s_waitcnt vmcnt(12)
	v_mul_f32_e32 v51, v51, v65
	v_fmac_f32_e32 v51, v50, v64
	v_mul_f32_e32 v50, v53, v67
	v_fmac_f32_e32 v50, v52, v66
	v_add_f32_e32 v50, v51, v50
	s_waitcnt vmcnt(11)
	v_mul_f32_e32 v47, v47, v65
	v_fmac_f32_e32 v47, v46, v64
	v_mul_f32_e32 v46, v49, v67
	v_fmac_f32_e32 v46, v48, v66
	v_add_f32_e32 v46, v47, v46
	s_waitcnt vmcnt(10)
	v_mul_f32_e32 v43, v43, v65
	v_fmac_f32_e32 v43, v42, v64
	v_mul_f32_e32 v42, v45, v67
	v_fmac_f32_e32 v42, v44, v66
	v_add_f32_e32 v42, v43, v42
	s_waitcnt vmcnt(9)
	v_mul_f32_e32 v39, v39, v65
	v_fmac_f32_e32 v39, v38, v64
	v_mul_f32_e32 v38, v41, v67
	v_fmac_f32_e32 v38, v40, v66
	v_add_f32_e32 v38, v39, v38
	s_waitcnt vmcnt(8)
	v_mul_f32_e32 v35, v35, v65
	v_fmac_f32_e32 v35, v34, v64
	v_mul_f32_e32 v34, v37, v67
	v_fmac_f32_e32 v34, v36, v66
	v_add_f32_e32 v34, v35, v34
	s_waitcnt vmcnt(7)
	v_mul_f32_e32 v31, v31, v65
	v_fmac_f32_e32 v31, v30, v64
	v_mul_f32_e32 v30, v33, v67
	v_fmac_f32_e32 v30, v32, v66
	v_add_f32_e32 v30, v31, v30
	s_waitcnt vmcnt(6)
	v_mul_f32_e32 v27, v27, v65
	v_fmac_f32_e32 v27, v26, v64
	v_mul_f32_e32 v26, v29, v67
	v_fmac_f32_e32 v26, v28, v66
	v_add_f32_e32 v26, v27, v26
	s_waitcnt vmcnt(5)
	v_mul_f32_e32 v23, v23, v65
	v_fmac_f32_e32 v23, v22, v64
	v_mul_f32_e32 v22, v25, v67
	v_fmac_f32_e32 v22, v24, v66
	v_add_f32_e32 v22, v23, v22
	s_waitcnt vmcnt(4)
	v_mul_f32_e32 v19, v19, v65
	v_fmac_f32_e32 v19, v18, v64
	v_mul_f32_e32 v18, v21, v67
	v_fmac_f32_e32 v18, v20, v66
	v_add_f32_e32 v18, v19, v18
	s_waitcnt vmcnt(3)
	v_mul_f32_e32 v15, v15, v65
	v_fmac_f32_e32 v15, v14, v64
	v_mul_f32_e32 v14, v17, v67
	v_fmac_f32_e32 v14, v16, v66
	v_add_f32_e32 v14, v15, v14
	s_waitcnt vmcnt(2)
	v_mul_f32_e32 v11, v11, v65
	v_fmac_f32_e32 v11, v10, v64
	v_mul_f32_e32 v10, v13, v67
	v_fmac_f32_e32 v10, v12, v66
	v_add_f32_e32 v10, v11, v10
	s_waitcnt vmcnt(1)
	v_mul_f32_e32 v7, v7, v65
	v_fmac_f32_e32 v7, v6, v64
	v_mul_f32_e32 v6, v9, v67
	v_fmac_f32_e32 v6, v8, v66
	v_add_f32_e32 v6, v7, v6
	s_waitcnt vmcnt(0)
	v_mul_f32_e32 v3, v3, v65
	v_fmac_f32_e32 v3, v2, v64
	v_mul_f32_e32 v2, v5, v67
	v_fmac_f32_e32 v2, v4, v66
	v_add_f32_e32 v2, v3, v2
	ds_bpermute_b32 v69, v200, v68
	ds_bpermute_b32 v59, v200, v58
	ds_bpermute_b32 v55, v200, v54
	ds_bpermute_b32 v51, v200, v50
	ds_bpermute_b32 v47, v200, v46
	ds_bpermute_b32 v43, v200, v42
	ds_bpermute_b32 v39, v200, v38
	ds_bpermute_b32 v35, v200, v34
	s_waitcnt lgkmcnt(7)
	v_add_f32_e32 v68, v68, v69
	s_waitcnt lgkmcnt(6)
	v_add_f32_e32 v58, v58, v59
	s_waitcnt lgkmcnt(5)
	v_add_f32_e32 v54, v54, v55
	s_waitcnt lgkmcnt(4)
	v_add_f32_e32 v50, v50, v51
	s_waitcnt lgkmcnt(3)
	v_add_f32_e32 v46, v46, v47
	s_waitcnt lgkmcnt(2)
	v_add_f32_e32 v42, v42, v43
	s_waitcnt lgkmcnt(1)
	v_add_f32_e32 v38, v38, v39
	s_waitcnt lgkmcnt(0)
	v_add_f32_e32 v34, v34, v35
	ds_bpermute_b32 v69, v201, v68
	ds_bpermute_b32 v59, v201, v58
	ds_bpermute_b32 v55, v201, v54
	ds_bpermute_b32 v51, v201, v50
	ds_bpermute_b32 v47, v201, v46
	ds_bpermute_b32 v43, v201, v42
	ds_bpermute_b32 v39, v201, v38
	ds_bpermute_b32 v35, v201, v34
	s_waitcnt lgkmcnt(7)
	v_add_f32_e32 v68, v68, v69
	s_waitcnt lgkmcnt(6)
	v_add_f32_e32 v58, v58, v59
	s_waitcnt lgkmcnt(5)
	v_add_f32_e32 v54, v54, v55
	s_waitcnt lgkmcnt(4)
	v_add_f32_e32 v50, v50, v51
	s_waitcnt lgkmcnt(3)
	v_add_f32_e32 v46, v46, v47
	s_waitcnt lgkmcnt(2)
	v_add_f32_e32 v42, v42, v43
	s_waitcnt lgkmcnt(1)
	v_add_f32_e32 v38, v38, v39
	s_waitcnt lgkmcnt(0)
	v_add_f32_e32 v34, v34, v35
	ds_bpermute_b32 v69, v202, v68
	ds_bpermute_b32 v59, v202, v58
	ds_bpermute_b32 v55, v202, v54
	ds_bpermute_b32 v51, v202, v50
	ds_bpermute_b32 v47, v202, v46
	ds_bpermute_b32 v43, v202, v42
	ds_bpermute_b32 v39, v202, v38
	ds_bpermute_b32 v35, v202, v34
	s_waitcnt lgkmcnt(7)
	v_add_f32_e32 v68, v68, v69
	s_waitcnt lgkmcnt(6)
	v_add_f32_e32 v58, v58, v59
	s_waitcnt lgkmcnt(5)
	v_add_f32_e32 v54, v54, v55
	s_waitcnt lgkmcnt(4)
	v_add_f32_e32 v50, v50, v51
	s_waitcnt lgkmcnt(3)
	v_add_f32_e32 v46, v46, v47
	s_waitcnt lgkmcnt(2)
	v_add_f32_e32 v42, v42, v43
	s_waitcnt lgkmcnt(1)
	v_add_f32_e32 v38, v38, v39
	s_waitcnt lgkmcnt(0)
	v_add_f32_e32 v34, v34, v35
	ds_bpermute_b32 v69, v203, v68
	ds_bpermute_b32 v59, v203, v58
	ds_bpermute_b32 v55, v203, v54
	ds_bpermute_b32 v51, v203, v50
	ds_bpermute_b32 v47, v203, v46
	ds_bpermute_b32 v43, v203, v42
	ds_bpermute_b32 v39, v203, v38
	ds_bpermute_b32 v35, v203, v34
	s_waitcnt lgkmcnt(7)
	v_add_f32_e32 v68, v68, v69
	s_waitcnt lgkmcnt(6)
	v_add_f32_e32 v58, v58, v59
	s_waitcnt lgkmcnt(5)
	v_add_f32_e32 v54, v54, v55
	s_waitcnt lgkmcnt(4)
	v_add_f32_e32 v50, v50, v51
	s_waitcnt lgkmcnt(3)
	v_add_f32_e32 v46, v46, v47
	s_waitcnt lgkmcnt(2)
	v_add_f32_e32 v42, v42, v43
	s_waitcnt lgkmcnt(1)
	v_add_f32_e32 v38, v38, v39
	s_waitcnt lgkmcnt(0)
	v_add_f32_e32 v34, v34, v35
	ds_bpermute_b32 v69, v204, v68
	ds_bpermute_b32 v59, v204, v58
	ds_bpermute_b32 v55, v204, v54
	ds_bpermute_b32 v51, v204, v50
	ds_bpermute_b32 v47, v204, v46
	ds_bpermute_b32 v43, v204, v42
	ds_bpermute_b32 v39, v204, v38
	ds_bpermute_b32 v35, v204, v34
	s_waitcnt lgkmcnt(7)
	v_add_f32_e32 v68, v68, v69
	s_waitcnt lgkmcnt(6)
	v_add_f32_e32 v58, v58, v59
	s_waitcnt lgkmcnt(5)
	v_add_f32_e32 v54, v54, v55
	s_waitcnt lgkmcnt(4)
	v_add_f32_e32 v50, v50, v51
	s_waitcnt lgkmcnt(3)
	v_add_f32_e32 v46, v46, v47
	s_waitcnt lgkmcnt(2)
	v_add_f32_e32 v42, v42, v43
	s_waitcnt lgkmcnt(1)
	v_add_f32_e32 v38, v38, v39
	s_waitcnt lgkmcnt(0)
	v_add_f32_e32 v34, v34, v35
	ds_bpermute_b32 v69, v205, v68
	ds_bpermute_b32 v59, v205, v58
	ds_bpermute_b32 v55, v205, v54
	ds_bpermute_b32 v51, v205, v50
	ds_bpermute_b32 v47, v205, v46
	ds_bpermute_b32 v43, v205, v42
	ds_bpermute_b32 v39, v205, v38
	ds_bpermute_b32 v35, v205, v34
	s_waitcnt lgkmcnt(7)
	v_add_f32_e32 v68, v68, v69
	s_waitcnt lgkmcnt(6)
	v_add_f32_e32 v58, v58, v59
	s_waitcnt lgkmcnt(5)
	v_add_f32_e32 v54, v54, v55
	s_waitcnt lgkmcnt(4)
	v_add_f32_e32 v50, v50, v51
	s_waitcnt lgkmcnt(3)
	v_add_f32_e32 v46, v46, v47
	s_waitcnt lgkmcnt(2)
	v_add_f32_e32 v42, v42, v43
	s_waitcnt lgkmcnt(1)
	v_add_f32_e32 v38, v38, v39
	s_waitcnt lgkmcnt(0)
	v_add_f32_e32 v34, v34, v35
	ds_bpermute_b32 v31, v200, v30
	ds_bpermute_b32 v27, v200, v26
	ds_bpermute_b32 v23, v200, v22
	ds_bpermute_b32 v19, v200, v18
	ds_bpermute_b32 v15, v200, v14
	ds_bpermute_b32 v11, v200, v10
	ds_bpermute_b32 v7, v200, v6
	ds_bpermute_b32 v3, v200, v2
	s_waitcnt lgkmcnt(7)
	v_add_f32_e32 v30, v30, v31
	s_waitcnt lgkmcnt(6)
	v_add_f32_e32 v26, v26, v27
	s_waitcnt lgkmcnt(5)
	v_add_f32_e32 v22, v22, v23
	s_waitcnt lgkmcnt(4)
	v_add_f32_e32 v18, v18, v19
	s_waitcnt lgkmcnt(3)
	v_add_f32_e32 v14, v14, v15
	s_waitcnt lgkmcnt(2)
	v_add_f32_e32 v10, v10, v11
	s_waitcnt lgkmcnt(1)
	v_add_f32_e32 v6, v6, v7
	s_waitcnt lgkmcnt(0)
	v_add_f32_e32 v2, v2, v3
	ds_bpermute_b32 v31, v201, v30
	ds_bpermute_b32 v27, v201, v26
	ds_bpermute_b32 v23, v201, v22
	ds_bpermute_b32 v19, v201, v18
	ds_bpermute_b32 v15, v201, v14
	ds_bpermute_b32 v11, v201, v10
	ds_bpermute_b32 v7, v201, v6
	ds_bpermute_b32 v3, v201, v2
	s_waitcnt lgkmcnt(7)
	v_add_f32_e32 v30, v30, v31
	s_waitcnt lgkmcnt(6)
	v_add_f32_e32 v26, v26, v27
	s_waitcnt lgkmcnt(5)
	v_add_f32_e32 v22, v22, v23
	s_waitcnt lgkmcnt(4)
	v_add_f32_e32 v18, v18, v19
	s_waitcnt lgkmcnt(3)
	v_add_f32_e32 v14, v14, v15
	s_waitcnt lgkmcnt(2)
	v_add_f32_e32 v10, v10, v11
	s_waitcnt lgkmcnt(1)
	v_add_f32_e32 v6, v6, v7
	s_waitcnt lgkmcnt(0)
	v_add_f32_e32 v2, v2, v3
	ds_bpermute_b32 v31, v202, v30
	ds_bpermute_b32 v27, v202, v26
	ds_bpermute_b32 v23, v202, v22
	ds_bpermute_b32 v19, v202, v18
	ds_bpermute_b32 v15, v202, v14
	ds_bpermute_b32 v11, v202, v10
	ds_bpermute_b32 v7, v202, v6
	ds_bpermute_b32 v3, v202, v2
	s_waitcnt lgkmcnt(7)
	v_add_f32_e32 v30, v30, v31
	s_waitcnt lgkmcnt(6)
	v_add_f32_e32 v26, v26, v27
	s_waitcnt lgkmcnt(5)
	v_add_f32_e32 v22, v22, v23
	s_waitcnt lgkmcnt(4)
	v_add_f32_e32 v18, v18, v19
	s_waitcnt lgkmcnt(3)
	v_add_f32_e32 v14, v14, v15
	s_waitcnt lgkmcnt(2)
	v_add_f32_e32 v10, v10, v11
	s_waitcnt lgkmcnt(1)
	v_add_f32_e32 v6, v6, v7
	s_waitcnt lgkmcnt(0)
	v_add_f32_e32 v2, v2, v3
	ds_bpermute_b32 v31, v203, v30
	ds_bpermute_b32 v27, v203, v26
	ds_bpermute_b32 v23, v203, v22
	ds_bpermute_b32 v19, v203, v18
	ds_bpermute_b32 v15, v203, v14
	ds_bpermute_b32 v11, v203, v10
	ds_bpermute_b32 v7, v203, v6
	ds_bpermute_b32 v3, v203, v2
	s_waitcnt lgkmcnt(7)
	v_add_f32_e32 v30, v30, v31
	s_waitcnt lgkmcnt(6)
	v_add_f32_e32 v26, v26, v27
	s_waitcnt lgkmcnt(5)
	v_add_f32_e32 v22, v22, v23
	s_waitcnt lgkmcnt(4)
	v_add_f32_e32 v18, v18, v19
	s_waitcnt lgkmcnt(3)
	v_add_f32_e32 v14, v14, v15
	s_waitcnt lgkmcnt(2)
	v_add_f32_e32 v10, v10, v11
	s_waitcnt lgkmcnt(1)
	v_add_f32_e32 v6, v6, v7
	s_waitcnt lgkmcnt(0)
	v_add_f32_e32 v2, v2, v3
	ds_bpermute_b32 v31, v204, v30
	ds_bpermute_b32 v27, v204, v26
	ds_bpermute_b32 v23, v204, v22
	ds_bpermute_b32 v19, v204, v18
	ds_bpermute_b32 v15, v204, v14
	ds_bpermute_b32 v11, v204, v10
	ds_bpermute_b32 v7, v204, v6
	ds_bpermute_b32 v3, v204, v2
	s_waitcnt lgkmcnt(7)
	v_add_f32_e32 v30, v30, v31
	s_waitcnt lgkmcnt(6)
	v_add_f32_e32 v26, v26, v27
	s_waitcnt lgkmcnt(5)
	v_add_f32_e32 v22, v22, v23
	s_waitcnt lgkmcnt(4)
	v_add_f32_e32 v18, v18, v19
	s_waitcnt lgkmcnt(3)
	v_add_f32_e32 v14, v14, v15
	s_waitcnt lgkmcnt(2)
	v_add_f32_e32 v10, v10, v11
	s_waitcnt lgkmcnt(1)
	v_add_f32_e32 v6, v6, v7
	s_waitcnt lgkmcnt(0)
	v_add_f32_e32 v2, v2, v3
	ds_bpermute_b32 v31, v205, v30
	ds_bpermute_b32 v27, v205, v26
	ds_bpermute_b32 v23, v205, v22
	ds_bpermute_b32 v19, v205, v18
	ds_bpermute_b32 v15, v205, v14
	ds_bpermute_b32 v11, v205, v10
	ds_bpermute_b32 v7, v205, v6
	ds_bpermute_b32 v3, v205, v2
	s_waitcnt lgkmcnt(7)
	v_add_f32_e32 v30, v30, v31
	s_waitcnt lgkmcnt(6)
	v_add_f32_e32 v26, v26, v27
	s_waitcnt lgkmcnt(5)
	v_add_f32_e32 v22, v22, v23
	s_waitcnt lgkmcnt(4)
	v_add_f32_e32 v18, v18, v19
	s_waitcnt lgkmcnt(3)
	v_add_f32_e32 v14, v14, v15
	s_waitcnt lgkmcnt(2)
	v_add_f32_e32 v10, v10, v11
	s_waitcnt lgkmcnt(1)
	v_add_f32_e32 v6, v6, v7
	s_waitcnt lgkmcnt(0)
	v_add_f32_e32 v2, v2, v3
	s_add_i32 s0, s84, s60
	v_mov_b32_e32 v69, s0
	s_and_saveexec_b64 vcc, s[14:15]
	ds_write_b32 v69, v68
	s_or_b64 exec, exec, vcc
	s_and_saveexec_b64 vcc, s[16:17]
	ds_write_b32 v69, v58 offset:4
	s_or_b64 exec, exec, vcc
	s_and_saveexec_b64 vcc, s[18:19]
	ds_write_b32 v69, v54 offset:8
	s_or_b64 exec, exec, vcc
	s_and_saveexec_b64 vcc, s[20:21]
	ds_write_b32 v69, v50 offset:12
	s_or_b64 exec, exec, vcc
	s_and_saveexec_b64 vcc, s[22:23]
	ds_write_b32 v69, v46 offset:16
	s_or_b64 exec, exec, vcc
	s_and_saveexec_b64 vcc, s[24:25]
	ds_write_b32 v69, v42 offset:20
	s_or_b64 exec, exec, vcc
	s_and_saveexec_b64 vcc, s[26:27]
	ds_write_b32 v69, v38 offset:24
	s_or_b64 exec, exec, vcc
	s_and_saveexec_b64 vcc, s[28:29]
	ds_write_b32 v69, v34 offset:28
	s_or_b64 exec, exec, vcc
	s_and_saveexec_b64 vcc, s[30:31]
	ds_write_b32 v69, v30 offset:32
	s_or_b64 exec, exec, vcc
	s_and_saveexec_b64 vcc, s[34:35]
	ds_write_b32 v69, v26 offset:36
	s_or_b64 exec, exec, vcc
	s_and_saveexec_b64 vcc, s[36:37]
	ds_write_b32 v69, v22 offset:40
	s_or_b64 exec, exec, vcc
	s_and_saveexec_b64 vcc, s[38:39]
	ds_write_b32 v69, v18 offset:44
	s_or_b64 exec, exec, vcc
	s_and_saveexec_b64 vcc, s[40:41]
	ds_write_b32 v69, v14 offset:48
	s_or_b64 exec, exec, vcc
	s_and_saveexec_b64 vcc, s[42:43]
	ds_write_b32 v69, v10 offset:52
	s_or_b64 exec, exec, vcc
	s_and_saveexec_b64 vcc, s[44:45]
	ds_write_b32 v69, v6 offset:56
	s_or_b64 exec, exec, vcc
	s_and_saveexec_b64 vcc, s[46:47]
	ds_write_b32 v69, v2 offset:60
	s_branch .LBB11_2192
